# v22 + residual stores interleaved into the residual-load pipeline (Wo, DN0, OUT epilogues)
# baseline (speedup 1.0000x reference)
; template <int MODE> DI void epilogue(const Epi& E, f32x4 (&acc)[2][2][4][2], const Unit& u, int wr, int wc, int fr, int fq) {
;     ...
;         for (int bj = 0; bj < 2; ++bj) {
;             const f32x4 g0 = *(const f32x4*)(E.gt + bidx * 6144 + col0 + bj * 32), g1 = *(const f32x4*)(E.gt + bidx * 6144 + col0 + bj * 32 + 4);
; #pragma unroll
;             for (int ai = 0; ai < 2; ++ai)
; #pragma unroll
;                 for (int m = 0; m < 4; ++m) {
;                     const unsigned off = E1_OFF(ai, m, bj);
;                     const f32x4 b0 = __builtin_nontemporal_load((const f32x4*)(base + off)), b1 = __builtin_nontemporal_load((const f32x4*)(base + off + 16));
;                     acc[ai][bj][m][0] = b0 + g0 * acc[ai][bj][m][0];
;                     acc[ai][bj][m][1] = b1 + g1 * acc[ai][bj][m][1];
;                     asm volatile("" : "+v"(acc[ai][bj][m][0]), "+v"(acc[ai][bj][m][1]));
;                 }
;             asm volatile("" ::: "memory");
;         }
; #pragma unroll
;         for (int ai = 0; ai < 2; ++ai)
; #pragma unroll
;             for (int m = 0; m < 4; ++m) {
;                 float sq = 0.f;
; #pragma unroll
;                 for (int bj = 0; bj < 2; ++bj)
; #pragma unroll
;                     for (int n = 0; n < 2; ++n) { const f32x4 v = acc[ai][bj][m][n]; sq += (v.x * v.x + v.y * v.y) + (v.z * v.z + v.w * v.w); }
;                 sq += __shfl_xor(sq, 16); sq += __shfl_xor(sq, 32);
;                 if (fq == 0) __hip_atomic_fetch_add(E.rowq + row0 + ai * HALF + m * 16, (1ull << 52) + (unsigned long long)(sq * 65536.0f + 0.5f), __ATOMIC_RELAXED, __HIP_MEMORY_SCOPE_AGENT);
;             }
;         if (!E.fin) {
;             char* outp = (char*)E.out;
; #pragma unroll
;             for (int bj = 0; bj < 2; ++bj)
; #pragma unroll
;                 for (int ai = 0; ai < 2; ++ai)
; #pragma unroll
;                     for (int m = 0; m < 4; ++m) {
;                         const unsigned off = E1_OFF(ai, m, bj);
;                         __builtin_nontemporal_store(acc[ai][bj][m][0], (f32x4*)(outp + off)); __builtin_nontemporal_store(acc[ai][bj][m][1], (f32x4*)(outp + off + 16));
;                     }
;         }
.LBB0_502:
	s_lshl_b32 s3, s8, 8
	v_add_u32_e32 v184, s3, v196
	s_add_i32 s3, s3, 0xffff0000
	s_lshr_b32 s3, s3, 12
	s_lshr_b32 s9, s8, 5
	s_add_i32 s3, s3, 8
	v_readlane_b32 s60, v254, 22
	s_cmpk_lt_i32 s8, 0x100
	v_readlane_b32 s61, v254, 23
	s_cselect_b32 s3, s9, s3
	s_mov_b64 s[8:9], s[60:61]
	v_readlane_b32 s25, v254, 58
	s_cselect_b32 s9, s9, s25
	v_readlane_b32 s25, v254, 56
	v_lshl_or_b32 v182, s2, 8, v198
	s_mul_i32 s2, s3, 0x1800
	s_cselect_b32 s8, s8, s25
	s_ashr_i32 s3, s2, 31
	s_lshl_b64 s[2:3], s[2:3], 2
	s_add_u32 s34, s47, s2
	v_lshlrev_b32_e32 v128, 2, v182
	v_ashrrev_i32_e32 v183, 31, v182
	s_addc_u32 s35, s48, s3
	v_lshl_add_u32 v144, v184, 12, v128
	v_lshl_add_u64 v[128:129], v[182:183], 2, s[34:35]
	global_load_dwordx4 v[130:133], v[128:129], off
	v_readlane_b32 s98, v254, 52
	v_readlane_b32 s99, v254, 53
	global_load_dwordx4 v[178:181], v[128:129], off offset:16
	global_load_dwordx4 v[186:189], v144, s[8:9] nt
	global_load_dwordx4 v[208:211], v144, s[8:9] offset:16 nt
	v_add_u32_e32 v175, 0x10000, v144
	global_load_dwordx4 v[212:215], v175, s[8:9] nt
	global_load_dwordx4 v[216:219], v175, s[8:9] offset:16 nt
	v_add_u32_e32 v173, 0x20000, v144
	global_load_dwordx4 v[220:223], v173, s[8:9] nt
	global_load_dwordx4 v[224:227], v173, s[8:9] offset:16 nt
	v_add_u32_e32 v175, 0x30000, v144
	global_load_dwordx4 v[240:243], v175, s[8:9] nt
	global_load_dwordx4 v[244:247], v175, s[8:9] offset:16 nt
	v_add_u32_e32 v166, 0x10000, v144
	v_add_u32_e32 v172, 0x20000, v144
	v_add_u32_e32 v176, 0x30000, v144
	v_add_u32_e32 v174, 0x90080, v144
	v_ashrrev_i32_e32 v185, 31, v184
	v_readlane_b32 s62, v254, 24
	v_readlane_b32 s63, v254, 25
	v_readlane_b32 s64, v254, 26
	v_readlane_b32 s65, v254, 27
	v_readlane_b32 s66, v254, 28
	v_readlane_b32 s67, v254, 29
	v_readlane_b32 s68, v254, 30
	v_readlane_b32 s69, v254, 31
	v_readlane_b32 s70, v254, 32
	v_readlane_b32 s71, v254, 33
	v_readlane_b32 s72, v254, 34
	v_readlane_b32 s73, v254, 35
	v_readlane_b32 s74, v254, 36
	v_readlane_b32 s75, v254, 37
	s_waitcnt vmcnt(7)
	v_pk_fma_f32 v[50:51], v[50:51], v[132:133], v[188:189]
	v_pk_fma_f32 v[48:49], v[48:49], v[130:131], v[186:187]
	s_waitcnt vmcnt(6)
	v_pk_fma_f32 v[30:31], v[30:31], v[180:181], v[210:211]
	v_pk_fma_f32 v[28:29], v[28:29], v[178:179], v[208:209]
	global_store_dwordx4 v144, v[48:51], s[98:99] nt
	global_store_dwordx4 v144, v[28:31], s[98:99] offset:16 nt
	v_add_u32_e32 v173, 0x80000, v144
	global_load_dwordx4 v[186:189], v173, s[8:9] nt
	global_load_dwordx4 v[208:211], v173, s[8:9] offset:16 nt
	s_nop 0
	s_waitcnt vmcnt(9)
	v_pk_fma_f32 v[70:71], v[70:71], v[132:133], v[214:215]
	v_pk_fma_f32 v[68:69], v[68:69], v[130:131], v[212:213]
	s_waitcnt vmcnt(8)
	v_pk_fma_f32 v[54:55], v[54:55], v[180:181], v[218:219]
	v_pk_fma_f32 v[52:53], v[52:53], v[178:179], v[216:217]
	v_add_u32_e32 v177, 0x10000, v144
	global_store_dwordx4 v177, v[68:71], s[98:99] nt
	global_store_dwordx4 v177, v[52:55], s[98:99] offset:16 nt
	v_add_u32_e32 v175, 0x90000, v144
	global_load_dwordx4 v[212:215], v175, s[8:9] nt
	global_load_dwordx4 v[216:219], v175, s[8:9] offset:16 nt
	s_nop 0
	s_waitcnt vmcnt(11)
	v_pk_fma_f32 v[86:87], v[86:87], v[132:133], v[222:223]
	v_pk_fma_f32 v[84:85], v[84:85], v[130:131], v[220:221]
	s_waitcnt vmcnt(10)
	v_pk_fma_f32 v[78:79], v[78:79], v[180:181], v[226:227]
	v_pk_fma_f32 v[76:77], v[76:77], v[178:179], v[224:225]
	v_add_u32_e32 v177, 0x20000, v144
	global_store_dwordx4 v177, v[84:87], s[98:99] nt
	global_store_dwordx4 v177, v[76:79], s[98:99] offset:16 nt
	v_add_u32_e32 v173, 0xa0000, v144
	global_load_dwordx4 v[220:223], v173, s[8:9] nt
	global_load_dwordx4 v[224:227], v173, s[8:9] offset:16 nt
	v_add_u32_e32 v156, 0x80000, v144
	v_add_u32_e32 v154, 0x10080, v144
	v_and_b32_e32 v157, 64, v202
	v_xor_b32_e32 v155, 16, v202
	v_add_u32_e32 v157, 64, v157
	v_cmp_lt_i32_e32 vcc, v155, v157
	s_waitcnt vmcnt(13)
	v_pk_fma_f32 v[98:99], v[98:99], v[132:133], v[242:243]
	v_pk_fma_f32 v[96:97], v[96:97], v[130:131], v[240:241]
	s_waitcnt vmcnt(12)
	v_pk_fma_f32 v[90:91], v[90:91], v[180:181], v[246:247]
	v_pk_fma_f32 v[88:89], v[88:89], v[178:179], v[244:245]
	v_add_u32_e32 v177, 0x30000, v144
	global_store_dwordx4 v177, v[96:99], s[98:99] nt
	global_store_dwordx4 v177, v[88:91], s[98:99] offset:16 nt
	v_add_u32_e32 v175, 0xb0000, v144
	global_load_dwordx4 v[240:243], v175, s[8:9] nt
	global_load_dwordx4 v[244:247], v175, s[8:9] offset:16 nt
	v_add_u32_e32 v160, 0x90000, v144
	v_add_u32_e32 v158, 0x20080, v144
	v_mul_f32_e32 v159, v49, v49
	v_mul_f32_e32 v161, v51, v51
	v_fmac_f32_e32 v159, v48, v48
	v_fmac_f32_e32 v161, v50, v50
	v_add_f32_e32 v159, v159, v161
	v_cndmask_b32_e32 v155, v202, v155, vcc
	v_lshlrev_b32_e32 v155, 2, v155
	s_waitcnt vmcnt(13)
	v_pk_fma_f32 v[114:115], v[114:115], v[132:133], v[188:189]
	v_pk_fma_f32 v[112:113], v[112:113], v[130:131], v[186:187]
	s_waitcnt vmcnt(12)
	v_pk_fma_f32 v[106:107], v[106:107], v[180:181], v[210:211]
	v_pk_fma_f32 v[104:105], v[104:105], v[178:179], v[208:209]
	v_add_u32_e32 v177, 0x80000, v144
	global_store_dwordx4 v177, v[112:115], s[98:99] nt
	global_store_dwordx4 v177, v[104:107], s[98:99] offset:16 nt
	global_load_dwordx4 v[186:189], v144, s[8:9] offset:128 nt
	global_load_dwordx4 v[208:211], v144, s[8:9] offset:144 nt
	v_add_u32_e32 v162, 0xa0000, v144
	v_add_u32_e32 v164, 0x30080, v144
	v_mul_f32_e32 v163, v29, v29
	v_mul_f32_e32 v165, v31, v31
	v_fmac_f32_e32 v163, v28, v28
	v_fmac_f32_e32 v165, v30, v30
	v_add_f32_e32 v161, v163, v165
	v_add_f32_e32 v159, v159, v161
	s_waitcnt vmcnt(13)
	v_pk_fma_f32 v[22:23], v[22:23], v[132:133], v[214:215]
	v_pk_fma_f32 v[20:21], v[20:21], v[130:131], v[212:213]
	s_waitcnt vmcnt(12)
; template <int MODE> DI void epilogue(const Epi& E, f32x4 (&acc)[2][2][4][2], const Unit& u, int wr, int wc, int fr, int fq) {
;     ...
;         for (int bj = 0; bj < 2; ++bj) {
;             const f32x4 g0 = *(const f32x4*)(E.gt + bidx * 6144 + col0 + bj * 32), g1 = *(const f32x4*)(E.gt + bidx * 6144 + col0 + bj * 32 + 4);
; #pragma unroll
;             for (int ai = 0; ai < 2; ++ai)
; #pragma unroll
;                 for (int m = 0; m < 4; ++m) {
;                     const unsigned off = E1_OFF(ai, m, bj);
;                     const f32x4 b0 = __builtin_nontemporal_load((const f32x4*)(base + off)), b1 = __builtin_nontemporal_load((const f32x4*)(base + off + 16));
;                     acc[ai][bj][m][0] = b0 + g0 * acc[ai][bj][m][0];
;                     acc[ai][bj][m][1] = b1 + g1 * acc[ai][bj][m][1];
;                     asm volatile("" : "+v"(acc[ai][bj][m][0]), "+v"(acc[ai][bj][m][1]));
;                 }
;             asm volatile("" ::: "memory");
;         }
; #pragma unroll
;         for (int ai = 0; ai < 2; ++ai)
; #pragma unroll
;             for (int m = 0; m < 4; ++m) {
;                 float sq = 0.f;
; #pragma unroll
;                 for (int bj = 0; bj < 2; ++bj)
; #pragma unroll
;                     for (int n = 0; n < 2; ++n) { const f32x4 v = acc[ai][bj][m][n]; sq += (v.x * v.x + v.y * v.y) + (v.z * v.z + v.w * v.w); }
;                 sq += __shfl_xor(sq, 16); sq += __shfl_xor(sq, 32);
;                 if (fq == 0) __hip_atomic_fetch_add(E.rowq + row0 + ai * HALF + m * 16, (1ull << 52) + (unsigned long long)(sq * 65536.0f + 0.5f), __ATOMIC_RELAXED, __HIP_MEMORY_SCOPE_AGENT);
;             }
;         if (!E.fin) {
;             char* outp = (char*)E.out;
; #pragma unroll
;             for (int bj = 0; bj < 2; ++bj)
; #pragma unroll
;                 for (int ai = 0; ai < 2; ++ai)
; #pragma unroll
;                     for (int m = 0; m < 4; ++m) {
;                         const unsigned off = E1_OFF(ai, m, bj);
;                         __builtin_nontemporal_store(acc[ai][bj][m][0], (f32x4*)(outp + off)); __builtin_nontemporal_store(acc[ai][bj][m][1], (f32x4*)(outp + off + 16));
;                     }
;         }
	v_pk_fma_f32 v[2:3], v[2:3], v[180:181], v[218:219]
	v_pk_fma_f32 v[0:1], v[0:1], v[178:179], v[216:217]
	v_add_u32_e32 v177, 0x90000, v144
	global_store_dwordx4 v177, v[20:23], s[98:99] nt
	global_store_dwordx4 v177, v[0:3], s[98:99] offset:16 nt
	v_add_u32_e32 v175, 0x10080, v144
	global_load_dwordx4 v[212:215], v175, s[8:9] nt
	global_load_dwordx4 v[216:219], v175, s[8:9] offset:16 nt
	v_add_u32_e32 v168, 0xb0000, v144
	v_add_u32_e32 v170, 0x80080, v144
	s_waitcnt vmcnt(13)
	v_pk_fma_f32 v[58:59], v[58:59], v[132:133], v[222:223]
	v_pk_fma_f32 v[56:57], v[56:57], v[130:131], v[220:221]
	s_waitcnt vmcnt(12)
	v_pk_fma_f32 v[38:39], v[38:39], v[180:181], v[226:227]
	v_pk_fma_f32 v[36:37], v[36:37], v[178:179], v[224:225]
	v_add_u32_e32 v177, 0xa0000, v144
	global_store_dwordx4 v177, v[56:59], s[98:99] nt
	global_store_dwordx4 v177, v[36:39], s[98:99] offset:16 nt
	v_add_u32_e32 v173, 0x20080, v144
	global_load_dwordx4 v[220:223], v173, s[8:9] nt
	global_load_dwordx4 v[224:227], v173, s[8:9] offset:16 nt
	s_nop 0
	s_waitcnt vmcnt(13)
	v_pk_fma_f32 v[10:11], v[10:11], v[132:133], v[242:243]
	v_pk_fma_f32 v[8:9], v[8:9], v[130:131], v[240:241]
	s_waitcnt vmcnt(12)
	v_pk_fma_f32 v[14:15], v[14:15], v[180:181], v[246:247]
	v_pk_fma_f32 v[12:13], v[12:13], v[178:179], v[244:245]
	v_add_u32_e32 v177, 0xb0000, v144
	global_store_dwordx4 v177, v[8:11], s[98:99] nt
	global_store_dwordx4 v177, v[12:15], s[98:99] offset:16 nt
	v_add_u32_e32 v175, 0x30080, v144
	global_load_dwordx4 v[240:243], v175, s[8:9] nt
	global_load_dwordx4 v[244:247], v175, s[8:9] offset:16 nt
	s_nop 0
	global_load_dwordx4 v[132:135], v[128:129], off offset:128
	s_nop 0
	global_load_dwordx4 v[128:131], v[128:129], off offset:144
	s_nop 0
	s_waitcnt vmcnt(1)
	v_pk_fma_f32 v[34:35], v[34:35], v[134:135], v[188:189]
	v_pk_fma_f32 v[32:33], v[32:33], v[132:133], v[186:187]
	s_waitcnt vmcnt(0)
	v_pk_fma_f32 v[18:19], v[18:19], v[130:131], v[210:211]
	v_pk_fma_f32 v[16:17], v[16:17], v[128:129], v[208:209]
	global_store_dwordx4 v144, v[32:35], s[98:99] offset:128 nt
	global_store_dwordx4 v144, v[16:19], s[98:99] offset:144 nt
	v_add_u32_e32 v173, 0x80080, v144
	global_load_dwordx4 v[186:189], v173, s[8:9] nt
	global_load_dwordx4 v[208:211], v173, s[8:9] offset:16 nt
	s_nop 0
	v_mul_f32_e32 v161, v33, v33
	v_mul_f32_e32 v163, v35, v35
	v_mul_f32_e32 v165, v17, v17
	v_mul_f32_e32 v167, v19, v19
	v_fmac_f32_e32 v161, v32, v32
	v_fmac_f32_e32 v163, v34, v34
	v_fmac_f32_e32 v165, v16, v16
	v_fmac_f32_e32 v167, v18, v18
	v_add_f32_e32 v161, v161, v163
	v_add_f32_e32 v163, v165, v167
	v_add_f32_e32 v159, v159, v161
	v_add_f32_e32 v159, v163, v159
	ds_bpermute_b32 v161, v155, v159
	v_xor_b32_e32 v163, 32, v202
	v_cmp_lt_i32_e32 vcc, v163, v157
	s_waitcnt lgkmcnt(0)
	v_add_f32_e32 v159, v159, v161
	v_cndmask_b32_e32 v157, v202, v163, vcc
	v_lshlrev_b32_e32 v157, 2, v157
	ds_bpermute_b32 v161, v157, v159
	v_pk_fma_f32 v[62:63], v[62:63], v[134:135], v[214:215]
	v_pk_fma_f32 v[60:61], v[60:61], v[132:133], v[212:213]
	v_pk_fma_f32 v[42:43], v[42:43], v[130:131], v[218:219]
	v_pk_fma_f32 v[40:41], v[40:41], v[128:129], v[216:217]
	v_add_u32_e32 v177, 0x10080, v144
	global_store_dwordx4 v177, v[60:63], s[98:99] nt
	global_store_dwordx4 v177, v[40:43], s[98:99] offset:16 nt
	v_add_u32_e32 v175, 0x90080, v144
	global_load_dwordx4 v[212:215], v175, s[8:9] nt
	global_load_dwordx4 v[216:219], v175, s[8:9] offset:16 nt
	s_nop 0
	v_pk_fma_f32 v[26:27], v[26:27], v[134:135], v[222:223]
	v_pk_fma_f32 v[24:25], v[24:25], v[132:133], v[220:221]
	v_pk_fma_f32 v[6:7], v[6:7], v[130:131], v[226:227]
	v_pk_fma_f32 v[4:5], v[4:5], v[128:129], v[224:225]
	v_add_u32_e32 v177, 0x20080, v144
	global_store_dwordx4 v177, v[24:27], s[98:99] nt
	global_store_dwordx4 v177, v[4:7], s[98:99] offset:16 nt
	v_add_u32_e32 v173, 0xa0080, v144
	global_load_dwordx4 v[220:223], v173, s[8:9] nt
	global_load_dwordx4 v[224:227], v173, s[8:9] offset:16 nt
	s_nop 0
	v_pk_fma_f32 v[66:67], v[66:67], v[134:135], v[242:243]
	v_pk_fma_f32 v[64:65], v[64:65], v[132:133], v[240:241]
	v_pk_fma_f32 v[46:47], v[46:47], v[130:131], v[246:247]
	v_pk_fma_f32 v[44:45], v[44:45], v[128:129], v[244:245]
	v_add_u32_e32 v177, 0x30080, v144
	global_store_dwordx4 v177, v[64:67], s[98:99] nt
	global_store_dwordx4 v177, v[44:47], s[98:99] offset:16 nt
	v_add_u32_e32 v175, 0xb0080, v144
	global_load_dwordx4 v[240:243], v175, s[8:9] nt
	global_load_dwordx4 v[244:247], v175, s[8:9] offset:16 nt
	s_nop 0
	s_waitcnt vmcnt(13)
	v_pk_fma_f32 v[82:83], v[82:83], v[134:135], v[188:189]
	v_pk_fma_f32 v[80:81], v[80:81], v[132:133], v[186:187]
	s_waitcnt vmcnt(12)
	v_pk_fma_f32 v[74:75], v[74:75], v[130:131], v[210:211]
	v_pk_fma_f32 v[72:73], v[72:73], v[128:129], v[208:209]
	v_add_u32_e32 v177, 0x80080, v144
	global_store_dwordx4 v177, v[80:83], s[98:99] nt
	global_store_dwordx4 v177, v[72:75], s[98:99] offset:16 nt
	v_add_u32_e32 v178, 0xa0080, v144
	v_add_u32_e32 v180, 0xb0080, v144
	s_waitcnt vmcnt(11)
	v_pk_fma_f32 v[102:103], v[102:103], v[134:135], v[214:215]
	v_pk_fma_f32 v[100:101], v[100:101], v[132:133], v[212:213]
	s_waitcnt vmcnt(10)
	v_pk_fma_f32 v[94:95], v[94:95], v[130:131], v[218:219]
	v_pk_fma_f32 v[92:93], v[92:93], v[128:129], v[216:217]
	v_add_u32_e32 v177, 0x90080, v144
	global_store_dwordx4 v177, v[100:103], s[98:99] nt
	global_store_dwordx4 v177, v[92:95], s[98:99] offset:16 nt
	s_nop 0
	s_waitcnt vmcnt(9)
	v_pk_fma_f32 v[118:119], v[118:119], v[134:135], v[222:223]
	v_pk_fma_f32 v[116:117], v[116:117], v[132:133], v[220:221]
	s_waitcnt vmcnt(8)
	v_pk_fma_f32 v[110:111], v[110:111], v[130:131], v[226:227]
	v_pk_fma_f32 v[108:109], v[108:109], v[128:129], v[224:225]
	v_add_u32_e32 v177, 0xa0080, v144
	global_store_dwordx4 v177, v[116:119], s[98:99] nt
	global_store_dwordx4 v177, v[108:111], s[98:99] offset:16 nt
	s_nop 0
	s_waitcnt vmcnt(7)
	v_pk_fma_f32 v[126:127], v[126:127], v[134:135], v[242:243]
	v_pk_fma_f32 v[124:125], v[124:125], v[132:133], v[240:241]
	s_waitcnt vmcnt(6)
	v_pk_fma_f32 v[122:123], v[122:123], v[130:131], v[246:247]
	v_pk_fma_f32 v[120:121], v[120:121], v[128:129], v[244:245]
	v_add_u32_e32 v177, 0xb0080, v144
	global_store_dwordx4 v177, v[124:127], s[98:99] nt
	global_store_dwordx4 v177, v[120:123], s[98:99] offset:16 nt
	s_waitcnt vmcnt(0)
	v_lshl_add_u64 v[128:129], v[184:185], 3, s[10:11]
	s_and_saveexec_b64 s[8:9], s[4:5]
	s_cbranch_execz .LBB0_504
	s_waitcnt lgkmcnt(0)
	v_add_f32_e32 v130, v159, v161
	v_fma_f32 v130, v130, s57, 0.5
	v_trunc_f32_e32 v130, v130
	v_mul_f32_e32 v131, 0x2f800000, v130
	v_floor_f32_e32 v131, v131
	v_fmac_f32_e32 v130, 0xcf800000, v131
	v_cvt_u32_f32_e32 v131, v131
	v_cvt_u32_f32_e32 v130, v130
	v_add_u32_e32 v131, 0x100000, v131
	global_atomic_add_x2 v[128:129], v[130:131], off

; template <int MODE> DI void epilogue(const Epi& E, f32x4 (&acc)[2][2][4][2], const Unit& u, int wr, int wc, int fr, int fq) {
;     ...
;         if (!E.fin) {
;             char* outp = (char*)E.out;
; #pragma unroll
;             for (int bj = 0; bj < 2; ++bj)
; #pragma unroll
;                 for (int ai = 0; ai < 2; ++ai)
; #pragma unroll
;                     for (int m = 0; m < 4; ++m) {
;                         const unsigned off = E1_OFF(ai, m, bj);
;                         __builtin_nontemporal_store(acc[ai][bj][m][0], (f32x4*)(outp + off)); __builtin_nontemporal_store(acc[ai][bj][m][1], (f32x4*)(outp + off + 16));
;                     }
;         }
.LBB0_518:
	s_or_b64 exec, exec, s[8:9]
	v_readlane_b32 s60, v254, 38
	v_mov_b32_e32 v167, v145
	v_readlane_b32 s74, v254, 52
	v_readlane_b32 s75, v254, 53
	v_mov_b32_e32 v173, v145
	v_mov_b32_e32 v177, v145
	s_waitcnt lgkmcnt(0)
	v_lshl_add_u64 v[130:131], s[74:75], 0, v[144:145]
	v_lshl_add_u64 v[132:133], s[74:75], 0, v[166:167]
	v_lshl_add_u64 v[132:133], s[74:75], 0, v[172:173]
	v_mov_b32_e32 v157, v145
	v_lshl_add_u64 v[132:133], s[74:75], 0, v[176:177]
	v_mov_b32_e32 v161, v145
	v_lshl_add_u64 v[132:133], s[74:75], 0, v[156:157]
	v_mov_b32_e32 v163, v145
	v_lshl_add_u64 v[132:133], s[74:75], 0, v[160:161]
	v_mov_b32_e32 v169, v145
	v_lshl_add_u64 v[132:133], s[74:75], 0, v[162:163]
	v_mov_b32_e32 v155, v145
	v_lshl_add_u64 v[132:133], s[74:75], 0, v[168:169]
	v_mov_b32_e32 v159, v145
	v_lshl_add_u64 v[130:131], s[74:75], 0, v[154:155]
	v_mov_b32_e32 v165, v145
	v_lshl_add_u64 v[130:131], s[74:75], 0, v[158:159]
	v_mov_b32_e32 v171, v145
	v_lshl_add_u64 v[130:131], s[74:75], 0, v[164:165]
	v_mov_b32_e32 v175, v145
	v_lshl_add_u64 v[130:131], s[74:75], 0, v[170:171]
	v_mov_b32_e32 v179, v145
	v_lshl_add_u64 v[130:131], s[74:75], 0, v[174:175]
	v_mov_b32_e32 v181, v145
	v_lshl_add_u64 v[130:131], s[74:75], 0, v[178:179]
	v_lshl_add_u64 v[130:131], s[74:75], 0, v[180:181]
	s_mov_b32 s25, 0
	v_readlane_b32 s61, v254, 39
	v_readlane_b32 s62, v254, 40
	v_readlane_b32 s63, v254, 41
	v_readlane_b32 s64, v254, 42
	v_readlane_b32 s65, v254, 43
	v_readlane_b32 s66, v254, 44
	v_readlane_b32 s67, v254, 45
	v_readlane_b32 s68, v254, 46
	v_readlane_b32 s69, v254, 47
	v_readlane_b32 s70, v254, 48
	v_readlane_b32 s71, v254, 49
	v_readlane_b32 s72, v254, 50
	v_readlane_b32 s73, v254, 51
	s_branch .LBB0_520

; template <int MODE> DI void epilogue(const Epi& E, f32x4 (&acc)[2][2][4][2], const Unit& u, int wr, int wc, int fr, int fq) {
;     ...
;         for (int bj = 0; bj < 2; ++bj) {
;             const f32x4 g0 = *(const f32x4*)(E.gt + bidx * 6144 + col0 + bj * 32), g1 = *(const f32x4*)(E.gt + bidx * 6144 + col0 + bj * 32 + 4);
; #pragma unroll
;             for (int ai = 0; ai < 2; ++ai)
; #pragma unroll
;                 for (int m = 0; m < 4; ++m) {
;                     const unsigned off = E1_OFF(ai, m, bj);
;                     const f32x4 b0 = __builtin_nontemporal_load((const f32x4*)(base + off)), b1 = __builtin_nontemporal_load((const f32x4*)(base + off + 16));
;                     acc[ai][bj][m][0] = b0 + g0 * acc[ai][bj][m][0];
;                     acc[ai][bj][m][1] = b1 + g1 * acc[ai][bj][m][1];
;                     asm volatile("" : "+v"(acc[ai][bj][m][0]), "+v"(acc[ai][bj][m][1]));
;                 }
;             asm volatile("" ::: "memory");
;         }
; #pragma unroll
;         for (int ai = 0; ai < 2; ++ai)
; #pragma unroll
;             for (int m = 0; m < 4; ++m) {
;                 float sq = 0.f;
; #pragma unroll
;                 for (int bj = 0; bj < 2; ++bj)
; #pragma unroll
;                     for (int n = 0; n < 2; ++n) { const f32x4 v = acc[ai][bj][m][n]; sq += (v.x * v.x + v.y * v.y) + (v.z * v.z + v.w * v.w); }
;                 sq += __shfl_xor(sq, 16); sq += __shfl_xor(sq, 32);
;                 if (fq == 0) __hip_atomic_fetch_add(E.rowq + row0 + ai * HALF + m * 16, (1ull << 52) + (unsigned long long)(sq * 65536.0f + 0.5f), __ATOMIC_RELAXED, __HIP_MEMORY_SCOPE_AGENT);
;             }
;         if (!E.fin) {
;             char* outp = (char*)E.out;
; #pragma unroll
;             for (int bj = 0; bj < 2; ++bj)
; #pragma unroll
;                 for (int ai = 0; ai < 2; ++ai)
; #pragma unroll
;                     for (int m = 0; m < 4; ++m) {
;                         const unsigned off = E1_OFF(ai, m, bj);
;                         __builtin_nontemporal_store(acc[ai][bj][m][0], (f32x4*)(outp + off)); __builtin_nontemporal_store(acc[ai][bj][m][1], (f32x4*)(outp + off + 16));
;                     }
;         }
.LBB0_668:
	s_lshl_b32 s8, s17, 8
	v_add_u32_e32 v184, s8, v191
	s_add_i32 s8, s8, 0xffff0000
	s_lshr_b32 s8, s8, 12
	s_lshr_b32 s9, s17, 5
	s_add_i32 s8, s8, 8
	s_cmpk_lt_i32 s17, 0x100
	s_cselect_b32 s8, s9, s8
	s_mulk_i32 s8, 0x1800
	s_ashr_i32 s9, s8, 31
	s_lshl_b64 s[38:39], s[8:9], 2
	v_lshl_or_b32 v180, s16, 8, v196
	s_add_u32 s8, s43, s38
	v_lshlrev_b32_e32 v128, 2, v180
	v_ashrrev_i32_e32 v181, 31, v180
	s_addc_u32 s9, s44, s39
	v_readlane_b32 s60, v254, 38
	v_lshl_add_u32 v144, v184, 12, v128
	v_lshl_add_u64 v[154:155], v[180:181], 2, s[8:9]
	v_readlane_b32 s74, v254, 52
	v_readlane_b32 s75, v254, 53
	global_load_dwordx4 v[128:131], v[154:155], off
	s_nop 3
	global_load_dwordx4 v[202:205], v[154:155], off offset:16
	global_load_dwordx4 v[186:189], v144, s[74:75] nt
	global_load_dwordx4 v[210:213], v144, s[74:75] offset:16 nt
	v_add_u32_e32 v175, 0x10000, v144
	global_load_dwordx4 v[214:217], v175, s[74:75] nt
	global_load_dwordx4 v[218:221], v175, s[74:75] offset:16 nt
	v_add_u32_e32 v173, 0x20000, v144
	global_load_dwordx4 v[222:225], v173, s[74:75] nt
	global_load_dwordx4 v[226:229], v173, s[74:75] offset:16 nt
	v_add_u32_e32 v175, 0x30000, v144
	global_load_dwordx4 v[240:243], v175, s[74:75] nt
	global_load_dwordx4 v[244:247], v175, s[74:75] offset:16 nt
	v_add_u32_e32 v166, 0x10000, v144
	v_add_u32_e32 v172, 0x20000, v144
	v_add_u32_e32 v176, 0x30000, v144
	v_add_u32_e32 v174, 0x90080, v144
	v_add_u32_e32 v178, 0xa0080, v144
	v_add_u32_e32 v182, 0xb0080, v144
	v_ashrrev_i32_e32 v185, 31, v184
	v_readlane_b32 s61, v254, 39
	v_readlane_b32 s62, v254, 40
	v_readlane_b32 s63, v254, 41
	v_readlane_b32 s64, v254, 42
	v_readlane_b32 s65, v254, 43
	v_readlane_b32 s66, v254, 44
	v_readlane_b32 s67, v254, 45
	v_readlane_b32 s68, v254, 46
	v_readlane_b32 s69, v254, 47
	v_readlane_b32 s70, v254, 48
	v_readlane_b32 s71, v254, 49
	v_readlane_b32 s72, v254, 50
	v_readlane_b32 s73, v254, 51
	s_waitcnt vmcnt(7)
	v_pk_fma_f32 v[50:51], v[50:51], v[130:131], v[188:189]
	v_pk_fma_f32 v[48:49], v[48:49], v[128:129], v[186:187]
	s_waitcnt vmcnt(6)
	v_pk_fma_f32 v[30:31], v[30:31], v[204:205], v[212:213]
	v_pk_fma_f32 v[28:29], v[28:29], v[202:203], v[210:211]
	global_store_dwordx4 v144, v[48:51], s[74:75] nt
	global_store_dwordx4 v144, v[28:31], s[74:75] offset:16 nt
	v_add_u32_e32 v173, 0x80000, v144
	global_load_dwordx4 v[186:189], v173, s[74:75] nt
	global_load_dwordx4 v[210:213], v173, s[74:75] offset:16 nt
	s_nop 0
	s_waitcnt vmcnt(9)
	v_pk_fma_f32 v[70:71], v[70:71], v[130:131], v[216:217]
	v_pk_fma_f32 v[68:69], v[68:69], v[128:129], v[214:215]
	s_waitcnt vmcnt(8)
	v_pk_fma_f32 v[54:55], v[54:55], v[204:205], v[220:221]
	v_pk_fma_f32 v[52:53], v[52:53], v[202:203], v[218:219]
	v_add_u32_e32 v177, 0x10000, v144
	global_store_dwordx4 v177, v[68:71], s[74:75] nt
	global_store_dwordx4 v177, v[52:55], s[74:75] offset:16 nt
	v_add_u32_e32 v175, 0x90000, v144
	global_load_dwordx4 v[214:217], v175, s[74:75] nt
	global_load_dwordx4 v[218:221], v175, s[74:75] offset:16 nt
	s_nop 0
	s_waitcnt vmcnt(11)
	v_pk_fma_f32 v[86:87], v[86:87], v[130:131], v[224:225]
	v_pk_fma_f32 v[84:85], v[84:85], v[128:129], v[222:223]
	s_waitcnt vmcnt(10)
	v_pk_fma_f32 v[78:79], v[78:79], v[204:205], v[228:229]
	v_pk_fma_f32 v[76:77], v[76:77], v[202:203], v[226:227]
	v_add_u32_e32 v177, 0x20000, v144
	global_store_dwordx4 v177, v[84:87], s[74:75] nt
	global_store_dwordx4 v177, v[76:79], s[74:75] offset:16 nt
	v_add_u32_e32 v173, 0xa0000, v144
	global_load_dwordx4 v[222:225], v173, s[74:75] nt
	global_load_dwordx4 v[226:229], v173, s[74:75] offset:16 nt
	v_add_u32_e32 v156, 0x80000, v144
	v_and_b32_e32 v157, 64, v200
	v_add_u32_e32 v157, 64, v157
	s_waitcnt vmcnt(13)
	v_pk_fma_f32 v[98:99], v[98:99], v[130:131], v[242:243]
	v_pk_fma_f32 v[96:97], v[96:97], v[128:129], v[240:241]
	s_waitcnt vmcnt(12)
	v_pk_fma_f32 v[90:91], v[90:91], v[204:205], v[246:247]
	v_pk_fma_f32 v[88:89], v[88:89], v[202:203], v[244:245]
	v_add_u32_e32 v177, 0x30000, v144
	global_store_dwordx4 v177, v[96:99], s[74:75] nt
	global_store_dwordx4 v177, v[88:91], s[74:75] offset:16 nt
	v_add_u32_e32 v175, 0xb0000, v144
	global_load_dwordx4 v[240:243], v175, s[74:75] nt
	global_load_dwordx4 v[244:247], v175, s[74:75] offset:16 nt
	v_add_u32_e32 v160, 0x90000, v144
	v_add_u32_e32 v158, 0x20080, v144
	v_mul_f32_e32 v159, v49, v49
	v_mul_f32_e32 v161, v51, v51
	v_fmac_f32_e32 v159, v48, v48
	v_fmac_f32_e32 v161, v50, v50
	v_add_f32_e32 v159, v159, v161
	s_waitcnt vmcnt(13)
	v_pk_fma_f32 v[114:115], v[114:115], v[130:131], v[188:189]
	v_pk_fma_f32 v[112:113], v[112:113], v[128:129], v[186:187]
	s_waitcnt vmcnt(12)
	v_pk_fma_f32 v[106:107], v[106:107], v[204:205], v[212:213]
	v_pk_fma_f32 v[104:105], v[104:105], v[202:203], v[210:211]
	v_add_u32_e32 v177, 0x80000, v144
	global_store_dwordx4 v177, v[112:115], s[74:75] nt
	global_store_dwordx4 v177, v[104:107], s[74:75] offset:16 nt
	global_load_dwordx4 v[186:189], v144, s[74:75] offset:128 nt
	global_load_dwordx4 v[210:213], v144, s[74:75] offset:144 nt
	v_add_u32_e32 v162, 0xa0000, v144
	v_add_u32_e32 v164, 0x30080, v144
	v_mul_f32_e32 v163, v29, v29
	v_mul_f32_e32 v165, v31, v31
	v_fmac_f32_e32 v163, v28, v28
	v_fmac_f32_e32 v165, v30, v30
	v_add_f32_e32 v161, v163, v165
	v_add_f32_e32 v159, v159, v161
	s_waitcnt vmcnt(13)
	v_pk_fma_f32 v[22:23], v[22:23], v[130:131], v[216:217]
	v_pk_fma_f32 v[20:21], v[20:21], v[128:129], v[214:215]
	s_waitcnt vmcnt(12)
; template <int MODE> DI void epilogue(const Epi& E, f32x4 (&acc)[2][2][4][2], const Unit& u, int wr, int wc, int fr, int fq) {
;     ...
;         for (int bj = 0; bj < 2; ++bj) {
;             const f32x4 g0 = *(const f32x4*)(E.gt + bidx * 6144 + col0 + bj * 32), g1 = *(const f32x4*)(E.gt + bidx * 6144 + col0 + bj * 32 + 4);
; #pragma unroll
;             for (int ai = 0; ai < 2; ++ai)
; #pragma unroll
;                 for (int m = 0; m < 4; ++m) {
;                     const unsigned off = E1_OFF(ai, m, bj);
;                     const f32x4 b0 = __builtin_nontemporal_load((const f32x4*)(base + off)), b1 = __builtin_nontemporal_load((const f32x4*)(base + off + 16));
;                     acc[ai][bj][m][0] = b0 + g0 * acc[ai][bj][m][0];
;                     acc[ai][bj][m][1] = b1 + g1 * acc[ai][bj][m][1];
;                     asm volatile("" : "+v"(acc[ai][bj][m][0]), "+v"(acc[ai][bj][m][1]));
;                 }
;             asm volatile("" ::: "memory");
;         }
; #pragma unroll
;         for (int ai = 0; ai < 2; ++ai)
; #pragma unroll
;             for (int m = 0; m < 4; ++m) {
;                 float sq = 0.f;
; #pragma unroll
;                 for (int bj = 0; bj < 2; ++bj)
; #pragma unroll
;                     for (int n = 0; n < 2; ++n) { const f32x4 v = acc[ai][bj][m][n]; sq += (v.x * v.x + v.y * v.y) + (v.z * v.z + v.w * v.w); }
;                 sq += __shfl_xor(sq, 16); sq += __shfl_xor(sq, 32);
;                 if (fq == 0) __hip_atomic_fetch_add(E.rowq + row0 + ai * HALF + m * 16, (1ull << 52) + (unsigned long long)(sq * 65536.0f + 0.5f), __ATOMIC_RELAXED, __HIP_MEMORY_SCOPE_AGENT);
;             }
;         if (!E.fin) {
;             char* outp = (char*)E.out;
; #pragma unroll
;             for (int bj = 0; bj < 2; ++bj)
; #pragma unroll
;                 for (int ai = 0; ai < 2; ++ai)
; #pragma unroll
;                     for (int m = 0; m < 4; ++m) {
;                         const unsigned off = E1_OFF(ai, m, bj);
;                         __builtin_nontemporal_store(acc[ai][bj][m][0], (f32x4*)(outp + off)); __builtin_nontemporal_store(acc[ai][bj][m][1], (f32x4*)(outp + off + 16));
;                     }
;         }
	v_pk_fma_f32 v[2:3], v[2:3], v[204:205], v[220:221]
	v_pk_fma_f32 v[0:1], v[0:1], v[202:203], v[218:219]
	v_add_u32_e32 v177, 0x90000, v144
	global_store_dwordx4 v177, v[20:23], s[74:75] nt
	global_store_dwordx4 v177, v[0:3], s[74:75] offset:16 nt
	v_add_u32_e32 v175, 0x10080, v144
	global_load_dwordx4 v[214:217], v175, s[74:75] nt
	global_load_dwordx4 v[218:221], v175, s[74:75] offset:16 nt
	v_add_u32_e32 v168, 0xb0000, v144
	v_add_u32_e32 v170, 0x80080, v144
	s_waitcnt vmcnt(13)
	v_pk_fma_f32 v[58:59], v[58:59], v[130:131], v[224:225]
	v_pk_fma_f32 v[56:57], v[56:57], v[128:129], v[222:223]
	s_waitcnt vmcnt(12)
	v_pk_fma_f32 v[38:39], v[38:39], v[204:205], v[228:229]
	v_pk_fma_f32 v[36:37], v[36:37], v[202:203], v[226:227]
	v_add_u32_e32 v177, 0xa0000, v144
	global_store_dwordx4 v177, v[56:59], s[74:75] nt
	global_store_dwordx4 v177, v[36:39], s[74:75] offset:16 nt
	v_add_u32_e32 v173, 0x20080, v144
	global_load_dwordx4 v[222:225], v173, s[74:75] nt
	global_load_dwordx4 v[226:229], v173, s[74:75] offset:16 nt
	s_nop 0
	s_waitcnt vmcnt(13)
	v_pk_fma_f32 v[10:11], v[10:11], v[130:131], v[242:243]
	v_pk_fma_f32 v[8:9], v[8:9], v[128:129], v[240:241]
	s_waitcnt vmcnt(12)
	v_pk_fma_f32 v[14:15], v[14:15], v[204:205], v[246:247]
	v_pk_fma_f32 v[12:13], v[12:13], v[202:203], v[244:245]
	v_add_u32_e32 v177, 0xb0000, v144
	global_store_dwordx4 v177, v[8:11], s[74:75] nt
	global_store_dwordx4 v177, v[12:15], s[74:75] offset:16 nt
	v_add_u32_e32 v175, 0x30080, v144
	global_load_dwordx4 v[240:243], v175, s[74:75] nt
	global_load_dwordx4 v[244:247], v175, s[74:75] offset:16 nt
	s_nop 0
	global_load_dwordx4 v[132:135], v[154:155], off offset:128
	global_load_dwordx4 v[128:131], v[154:155], off offset:144
	v_add_u32_e32 v154, 0x10080, v144
	v_xor_b32_e32 v155, 16, v200
	v_cmp_lt_i32_e32 vcc, v155, v157
	s_waitcnt vmcnt(1)
	v_pk_fma_f32 v[34:35], v[34:35], v[134:135], v[188:189]
	v_pk_fma_f32 v[32:33], v[32:33], v[132:133], v[186:187]
	s_waitcnt vmcnt(0)
	v_pk_fma_f32 v[18:19], v[18:19], v[130:131], v[212:213]
	v_pk_fma_f32 v[16:17], v[16:17], v[128:129], v[210:211]
	global_store_dwordx4 v144, v[32:35], s[74:75] offset:128 nt
	global_store_dwordx4 v144, v[16:19], s[74:75] offset:144 nt
	v_add_u32_e32 v173, 0x80080, v144
	global_load_dwordx4 v[186:189], v173, s[74:75] nt
	global_load_dwordx4 v[210:213], v173, s[74:75] offset:16 nt
	v_cndmask_b32_e32 v155, v200, v155, vcc
	v_mul_f32_e32 v161, v33, v33
	v_mul_f32_e32 v163, v35, v35
	v_mul_f32_e32 v165, v17, v17
	v_mul_f32_e32 v167, v19, v19
	v_fmac_f32_e32 v161, v32, v32
	v_fmac_f32_e32 v163, v34, v34
	v_fmac_f32_e32 v165, v16, v16
	v_fmac_f32_e32 v167, v18, v18
	v_add_f32_e32 v161, v161, v163
	v_add_f32_e32 v163, v165, v167
	v_add_f32_e32 v159, v159, v161
	v_lshlrev_b32_e32 v155, 2, v155
	v_add_f32_e32 v159, v163, v159
	ds_bpermute_b32 v161, v155, v159
	v_xor_b32_e32 v163, 32, v200
	v_cmp_lt_i32_e32 vcc, v163, v157
	s_waitcnt lgkmcnt(0)
	v_add_f32_e32 v159, v159, v161
	v_cndmask_b32_e32 v157, v200, v163, vcc
	v_lshlrev_b32_e32 v157, 2, v157
	ds_bpermute_b32 v161, v157, v159
	v_pk_fma_f32 v[62:63], v[62:63], v[134:135], v[216:217]
	v_pk_fma_f32 v[60:61], v[60:61], v[132:133], v[214:215]
	v_pk_fma_f32 v[42:43], v[42:43], v[130:131], v[220:221]
	v_pk_fma_f32 v[40:41], v[40:41], v[128:129], v[218:219]
	v_add_u32_e32 v177, 0x10080, v144
	global_store_dwordx4 v177, v[60:63], s[74:75] nt
	global_store_dwordx4 v177, v[40:43], s[74:75] offset:16 nt
	v_add_u32_e32 v175, 0x90080, v144
	global_load_dwordx4 v[214:217], v175, s[74:75] nt
	global_load_dwordx4 v[218:221], v175, s[74:75] offset:16 nt
	s_nop 0
	v_pk_fma_f32 v[26:27], v[26:27], v[134:135], v[224:225]
	v_pk_fma_f32 v[24:25], v[24:25], v[132:133], v[222:223]
	v_pk_fma_f32 v[6:7], v[6:7], v[130:131], v[228:229]
	v_pk_fma_f32 v[4:5], v[4:5], v[128:129], v[226:227]
	v_add_u32_e32 v177, 0x20080, v144
	global_store_dwordx4 v177, v[24:27], s[74:75] nt
	global_store_dwordx4 v177, v[4:7], s[74:75] offset:16 nt
	v_add_u32_e32 v173, 0xa0080, v144
	global_load_dwordx4 v[222:225], v173, s[74:75] nt
	global_load_dwordx4 v[226:229], v173, s[74:75] offset:16 nt
	s_nop 0
	v_pk_fma_f32 v[66:67], v[66:67], v[134:135], v[242:243]
	v_pk_fma_f32 v[64:65], v[64:65], v[132:133], v[240:241]
	v_pk_fma_f32 v[46:47], v[46:47], v[130:131], v[246:247]
	v_pk_fma_f32 v[44:45], v[44:45], v[128:129], v[244:245]
	v_add_u32_e32 v177, 0x30080, v144
	global_store_dwordx4 v177, v[64:67], s[74:75] nt
	global_store_dwordx4 v177, v[44:47], s[74:75] offset:16 nt
	v_add_u32_e32 v175, 0xb0080, v144
	global_load_dwordx4 v[240:243], v175, s[74:75] nt
	global_load_dwordx4 v[244:247], v175, s[74:75] offset:16 nt
	s_nop 0
	s_waitcnt vmcnt(13)
	v_pk_fma_f32 v[82:83], v[82:83], v[134:135], v[188:189]
	v_pk_fma_f32 v[80:81], v[80:81], v[132:133], v[186:187]
	s_waitcnt vmcnt(12)
	v_pk_fma_f32 v[74:75], v[74:75], v[130:131], v[212:213]
	v_pk_fma_f32 v[72:73], v[72:73], v[128:129], v[210:211]
	v_add_u32_e32 v177, 0x80080, v144
	global_store_dwordx4 v177, v[80:83], s[74:75] nt
	global_store_dwordx4 v177, v[72:75], s[74:75] offset:16 nt
	s_nop 0
	s_waitcnt vmcnt(11)
	v_pk_fma_f32 v[102:103], v[102:103], v[134:135], v[216:217]
	v_pk_fma_f32 v[100:101], v[100:101], v[132:133], v[214:215]
	s_waitcnt vmcnt(10)
	v_pk_fma_f32 v[94:95], v[94:95], v[130:131], v[220:221]
	v_pk_fma_f32 v[92:93], v[92:93], v[128:129], v[218:219]
	v_add_u32_e32 v177, 0x90080, v144
	global_store_dwordx4 v177, v[100:103], s[74:75] nt
	global_store_dwordx4 v177, v[92:95], s[74:75] offset:16 nt
	s_nop 0
	s_waitcnt vmcnt(9)
	v_pk_fma_f32 v[118:119], v[118:119], v[134:135], v[224:225]
	v_pk_fma_f32 v[116:117], v[116:117], v[132:133], v[222:223]
	s_waitcnt vmcnt(8)
	v_pk_fma_f32 v[110:111], v[110:111], v[130:131], v[228:229]
	v_pk_fma_f32 v[108:109], v[108:109], v[128:129], v[226:227]
	v_add_u32_e32 v177, 0xa0080, v144
	global_store_dwordx4 v177, v[116:119], s[74:75] nt
	global_store_dwordx4 v177, v[108:111], s[74:75] offset:16 nt
	s_nop 0
	s_waitcnt vmcnt(7)
	v_pk_fma_f32 v[126:127], v[126:127], v[134:135], v[242:243]
	v_pk_fma_f32 v[124:125], v[124:125], v[132:133], v[240:241]
	s_waitcnt vmcnt(6)
	v_pk_fma_f32 v[122:123], v[122:123], v[130:131], v[246:247]
	v_pk_fma_f32 v[120:121], v[120:121], v[128:129], v[244:245]
	v_add_u32_e32 v177, 0xb0080, v144
	global_store_dwordx4 v177, v[124:127], s[74:75] nt
	global_store_dwordx4 v177, v[120:123], s[74:75] offset:16 nt
	s_waitcnt vmcnt(0)
	v_lshl_add_u64 v[128:129], v[184:185], 3, s[2:3]
	s_and_saveexec_b64 s[8:9], s[4:5]
	s_cbranch_execz .LBB0_670
	s_waitcnt lgkmcnt(0)
	v_add_f32_e32 v130, v159, v161
	v_fma_f32 v130, v130, s54, 0.5
	v_trunc_f32_e32 v130, v130
	v_mul_f32_e32 v131, 0x2f800000, v130
	v_floor_f32_e32 v131, v131
	v_fmac_f32_e32 v130, 0xcf800000, v131
	v_cvt_u32_f32_e32 v131, v131
	v_cvt_u32_f32_e32 v130, v130
	v_add_u32_e32 v131, 0x100000, v131
	global_atomic_add_x2 v[128:129], v[130:131], off

; template <int MODE> DI void epilogue(const Epi& E, f32x4 (&acc)[2][2][4][2], const Unit& u, int wr, int wc, int fr, int fq) {
;     ...
;         if (!E.fin) {
;             char* outp = (char*)E.out;
; #pragma unroll
;             for (int bj = 0; bj < 2; ++bj)
; #pragma unroll
;                 for (int ai = 0; ai < 2; ++ai)
; #pragma unroll
;                     for (int m = 0; m < 4; ++m) {
;                         const unsigned off = E1_OFF(ai, m, bj);
;                         __builtin_nontemporal_store(acc[ai][bj][m][0], (f32x4*)(outp + off)); __builtin_nontemporal_store(acc[ai][bj][m][1], (f32x4*)(outp + off + 16));
;                     }
;         }
.LBB0_684:
	s_or_b64 exec, exec, s[8:9]
	v_readlane_b32 s60, v254, 38
	v_readlane_b32 s74, v254, 52
	v_readlane_b32 s75, v254, 53
	v_mov_b32_e32 v167, v145
	v_mov_b32_e32 v173, v145
	v_mov_b32_e32 v177, v145
	v_mov_b32_e32 v157, v145
	v_mov_b32_e32 v161, v145
	s_waitcnt lgkmcnt(0)
	v_lshl_add_u64 v[130:131], s[74:75], 0, v[144:145]
	v_lshl_add_u64 v[132:133], s[74:75], 0, v[166:167]
	v_lshl_add_u64 v[134:135], s[74:75], 0, v[172:173]
	v_lshl_add_u64 v[184:185], s[74:75], 0, v[176:177]
	v_lshl_add_u64 v[186:187], s[74:75], 0, v[156:157]
	v_lshl_add_u64 v[188:189], s[74:75], 0, v[160:161]
	v_mov_b32_e32 v163, v145
	v_mov_b32_e32 v169, v145
	v_mov_b32_e32 v155, v145
	v_mov_b32_e32 v159, v145
	v_mov_b32_e32 v165, v145
	v_mov_b32_e32 v171, v145
	v_mov_b32_e32 v175, v145
	v_mov_b32_e32 v179, v145
	v_mov_b32_e32 v183, v145
	s_mov_b32 s58, 0
	v_readlane_b32 s61, v254, 39
	v_readlane_b32 s62, v254, 40
	v_readlane_b32 s63, v254, 41
	v_readlane_b32 s64, v254, 42
	v_readlane_b32 s65, v254, 43
	v_readlane_b32 s66, v254, 44
	v_readlane_b32 s67, v254, 45
	v_readlane_b32 s68, v254, 46
	v_readlane_b32 s69, v254, 47
	v_readlane_b32 s70, v254, 48
	v_readlane_b32 s71, v254, 49
	v_readlane_b32 s72, v254, 50
	v_readlane_b32 s73, v254, 51
	v_lshl_add_u64 v[194:195], s[74:75], 0, v[162:163]
	v_lshl_add_u64 v[202:203], s[74:75], 0, v[168:169]
	v_lshl_add_u64 v[204:205], s[74:75], 0, v[154:155]
	v_lshl_add_u64 v[206:207], s[74:75], 0, v[158:159]
	v_lshl_add_u64 v[208:209], s[74:75], 0, v[164:165]
	v_lshl_add_u64 v[210:211], s[74:75], 0, v[170:171]
	v_lshl_add_u64 v[212:213], s[74:75], 0, v[174:175]
	v_lshl_add_u64 v[214:215], s[74:75], 0, v[178:179]
	v_lshl_add_u64 v[216:217], s[74:75], 0, v[182:183]
	s_branch .LBB0_686

; template <int MODE> DI void epilogue(const Epi& E, f32x4 (&acc)[2][2][4][2], const Unit& u, int wr, int wc, int fr, int fq) {
;     ...
;         const int bidx = batch_of_row(u.pm * BM);
;         const char* base = (const char*)((u.pm * BM < TP) ? E.base_p : E.base_s);
;         const int col0 = u.pn * BM + wc * 64 + 8 * fq;
;         const unsigned ro = ((unsigned)row0 * D + (unsigned)col0) * 4u;
;     ...
; #pragma unroll
;         for (int bj = 0; bj < 2; ++bj) {
;             const f32x4 g0 = *(const f32x4*)(E.gt + bidx * 6144 + col0 + bj * 32), g1 = *(const f32x4*)(E.gt + bidx * 6144 + col0 + bj * 32 + 4);
; #pragma unroll
;             for (int ai = 0; ai < 2; ++ai)
; #pragma unroll
;                 for (int m = 0; m < 4; ++m) {
;                     const unsigned off = E1_OFF(ai, m, bj);
;                     const f32x4 b0 = __builtin_nontemporal_load((const f32x4*)(base + off)), b1 = __builtin_nontemporal_load((const f32x4*)(base + off + 16));
;                     acc[ai][bj][m][0] = b0 + g0 * acc[ai][bj][m][0];
;                     acc[ai][bj][m][1] = b1 + g1 * acc[ai][bj][m][1];
;                     asm volatile("" : "+v"(acc[ai][bj][m][0]), "+v"(acc[ai][bj][m][1]));
;                 }
;             asm volatile("" ::: "memory");
;         }
; #pragma unroll
;         for (int ai = 0; ai < 2; ++ai)
; #pragma unroll
;             for (int m = 0; m < 4; ++m) {
;                 float sq = 0.f;
; #pragma unroll
;                 for (int bj = 0; bj < 2; ++bj)
; #pragma unroll
;                     for (int n = 0; n < 2; ++n) { const f32x4 v = acc[ai][bj][m][n]; sq += (v.x * v.x + v.y * v.y) + (v.z * v.z + v.w * v.w); }
;                 sq += __shfl_xor(sq, 16); sq += __shfl_xor(sq, 32);
;                 if (fq == 0) __hip_atomic_fetch_add(E.rowq + row0 + ai * HALF + m * 16, (1ull << 52) + (unsigned long long)(sq * 65536.0f + 0.5f), __ATOMIC_RELAXED, __HIP_MEMORY_SCOPE_AGENT);
;             }
;         if (!E.fin) {
;             char* outp = (char*)E.out;
; #pragma unroll
;             for (int bj = 0; bj < 2; ++bj)
; #pragma unroll
;                 for (int ai = 0; ai < 2; ++ai)
; #pragma unroll
;                     for (int m = 0; m < 4; ++m) {
;                         const unsigned off = E1_OFF(ai, m, bj);
.LBB0_999:
	s_lshl_b32 s9, s10, 8
	v_add_u32_e32 v184, s9, v191
	s_add_i32 s9, s9, 0xffff0000
	s_lshr_b32 s9, s9, 12
	s_lshr_b32 s11, s10, 5
	s_add_i32 s9, s9, 8
	s_cmpk_lt_i32 s10, 0x100
	s_cselect_b32 s9, s11, s9
	v_lshl_or_b32 v180, s8, 8, v196
	s_mul_i32 s8, s9, 0x1800
	s_ashr_i32 s9, s8, 31
	s_lshl_b64 s[42:43], s[8:9], 2
	s_add_u32 s8, s47, s42
	v_lshlrev_b32_e32 v128, 2, v180
	v_ashrrev_i32_e32 v181, 31, v180
	s_addc_u32 s9, s48, s43
	v_readlane_b32 s72, v254, 38
	v_lshl_add_u32 v144, v184, 12, v128
	v_lshl_add_u64 v[154:155], v[180:181], 2, s[8:9]
	v_readlane_b32 s86, v254, 52
	v_readlane_b32 s87, v254, 53
	global_load_dwordx4 v[128:131], v[154:155], off
	s_nop 3
	global_load_dwordx4 v[176:179], v[154:155], off offset:16
	global_load_dwordx4 v[186:189], v144, s[86:87] nt
	global_load_dwordx4 v[210:213], v144, s[86:87] offset:16 nt
	v_add_u32_e32 v171, 0x10000, v144
	global_load_dwordx4 v[214:217], v171, s[86:87] nt
	global_load_dwordx4 v[218:221], v171, s[86:87] offset:16 nt
	v_add_u32_e32 v169, 0x20000, v144
	global_load_dwordx4 v[222:225], v169, s[86:87] nt
	global_load_dwordx4 v[226:229], v169, s[86:87] offset:16 nt
	v_add_u32_e32 v171, 0x30000, v144
	global_load_dwordx4 v[240:243], v171, s[86:87] nt
	global_load_dwordx4 v[244:247], v171, s[86:87] offset:16 nt
	v_add_u32_e32 v166, 0x10000, v144
	v_add_u32_e32 v170, 0x20000, v144
	v_add_u32_e32 v174, 0x30000, v144
	v_add_u32_e32 v168, 0xb0000, v144
	v_add_u32_e32 v172, 0x80080, v144
	v_add_u32_e32 v182, 0xb0080, v144
	v_ashrrev_i32_e32 v185, 31, v184
	v_readlane_b32 s73, v254, 39
	v_readlane_b32 s74, v254, 40
	v_readlane_b32 s75, v254, 41
	v_readlane_b32 s76, v254, 42
	v_readlane_b32 s77, v254, 43
	v_readlane_b32 s78, v254, 44
	v_readlane_b32 s79, v254, 45
	v_readlane_b32 s80, v254, 46
	v_readlane_b32 s81, v254, 47
	v_readlane_b32 s82, v254, 48
	v_readlane_b32 s83, v254, 49
	v_readlane_b32 s84, v254, 50
	v_readlane_b32 s85, v254, 51
	s_waitcnt vmcnt(7)
	v_pk_fma_f32 v[38:39], v[38:39], v[130:131], v[188:189]
	v_pk_fma_f32 v[36:37], v[36:37], v[128:129], v[186:187]
	s_waitcnt vmcnt(6)
	v_pk_fma_f32 v[22:23], v[22:23], v[178:179], v[212:213]
	v_pk_fma_f32 v[20:21], v[20:21], v[176:177], v[210:211]
	global_store_dwordx4 v144, v[36:39], s[86:87] nt
	global_store_dwordx4 v144, v[20:23], s[86:87] offset:16 nt
	v_add_u32_e32 v169, 0x80000, v144
	global_load_dwordx4 v[186:189], v169, s[86:87] nt
	global_load_dwordx4 v[210:213], v169, s[86:87] offset:16 nt
	s_nop 0
	s_waitcnt vmcnt(9)
	v_pk_fma_f32 v[62:63], v[62:63], v[130:131], v[216:217]
	v_pk_fma_f32 v[60:61], v[60:61], v[128:129], v[214:215]
	s_waitcnt vmcnt(8)
	v_pk_fma_f32 v[46:47], v[46:47], v[178:179], v[220:221]
	v_pk_fma_f32 v[44:45], v[44:45], v[176:177], v[218:219]
	v_add_u32_e32 v173, 0x10000, v144
	global_store_dwordx4 v173, v[60:63], s[86:87] nt
	global_store_dwordx4 v173, v[44:47], s[86:87] offset:16 nt
	v_add_u32_e32 v171, 0x90000, v144
	global_load_dwordx4 v[214:217], v171, s[86:87] nt
	global_load_dwordx4 v[218:221], v171, s[86:87] offset:16 nt
	s_nop 0
	s_waitcnt vmcnt(11)
	v_pk_fma_f32 v[82:83], v[82:83], v[130:131], v[224:225]
	v_pk_fma_f32 v[80:81], v[80:81], v[128:129], v[222:223]
	s_waitcnt vmcnt(10)
	v_pk_fma_f32 v[74:75], v[74:75], v[178:179], v[228:229]
	v_pk_fma_f32 v[72:73], v[72:73], v[176:177], v[226:227]
	v_add_u32_e32 v173, 0x20000, v144
	global_store_dwordx4 v173, v[80:83], s[86:87] nt
	global_store_dwordx4 v173, v[72:75], s[86:87] offset:16 nt
	v_add_u32_e32 v169, 0xa0000, v144
	global_load_dwordx4 v[222:225], v169, s[86:87] nt
	global_load_dwordx4 v[226:229], v169, s[86:87] offset:16 nt
	v_add_u32_e32 v156, 0x80000, v144
	v_and_b32_e32 v157, 64, v200
	v_add_u32_e32 v157, 64, v157
	s_waitcnt vmcnt(13)
	v_pk_fma_f32 v[98:99], v[98:99], v[130:131], v[242:243]
	v_pk_fma_f32 v[96:97], v[96:97], v[128:129], v[240:241]
	s_waitcnt vmcnt(12)
	v_pk_fma_f32 v[90:91], v[90:91], v[178:179], v[246:247]
	v_pk_fma_f32 v[88:89], v[88:89], v[176:177], v[244:245]
	v_add_u32_e32 v173, 0x30000, v144
	global_store_dwordx4 v173, v[96:99], s[86:87] nt
	global_store_dwordx4 v173, v[88:91], s[86:87] offset:16 nt
	v_add_u32_e32 v171, 0xb0000, v144
	global_load_dwordx4 v[240:243], v171, s[86:87] nt
	global_load_dwordx4 v[244:247], v171, s[86:87] offset:16 nt
	v_add_u32_e32 v160, 0x90000, v144
	v_add_u32_e32 v158, 0x20080, v144
	v_mul_f32_e32 v159, v37, v37
	v_mul_f32_e32 v161, v39, v39
	v_fmac_f32_e32 v159, v36, v36
	v_fmac_f32_e32 v161, v38, v38
	v_add_f32_e32 v159, v159, v161
	s_waitcnt vmcnt(13)
	v_pk_fma_f32 v[114:115], v[114:115], v[130:131], v[188:189]
	v_pk_fma_f32 v[112:113], v[112:113], v[128:129], v[186:187]
	s_waitcnt vmcnt(12)
	v_pk_fma_f32 v[106:107], v[106:107], v[178:179], v[212:213]
	v_pk_fma_f32 v[104:105], v[104:105], v[176:177], v[210:211]
	v_add_u32_e32 v173, 0x80000, v144
	global_store_dwordx4 v173, v[112:115], s[86:87] nt
	global_store_dwordx4 v173, v[104:107], s[86:87] offset:16 nt
	global_load_dwordx4 v[186:189], v144, s[86:87] offset:128 nt
	global_load_dwordx4 v[210:213], v144, s[86:87] offset:144 nt
	v_add_u32_e32 v162, 0xa0000, v144
	v_add_u32_e32 v164, 0x30080, v144
	v_mul_f32_e32 v163, v21, v21
	v_mul_f32_e32 v165, v23, v23
	v_fmac_f32_e32 v163, v20, v20
	v_fmac_f32_e32 v165, v22, v22
	v_add_f32_e32 v161, v163, v165
	v_add_f32_e32 v159, v159, v161
	s_waitcnt vmcnt(13)
	v_pk_fma_f32 v[26:27], v[26:27], v[130:131], v[216:217]
	v_pk_fma_f32 v[24:25], v[24:25], v[128:129], v[214:215]
	s_waitcnt vmcnt(12)
; template <int MODE> DI void epilogue(const Epi& E, f32x4 (&acc)[2][2][4][2], const Unit& u, int wr, int wc, int fr, int fq) {
;     ...
;         for (int bj = 0; bj < 2; ++bj) {
;             const f32x4 g0 = *(const f32x4*)(E.gt + bidx * 6144 + col0 + bj * 32), g1 = *(const f32x4*)(E.gt + bidx * 6144 + col0 + bj * 32 + 4);
; #pragma unroll
;             for (int ai = 0; ai < 2; ++ai)
; #pragma unroll
;                 for (int m = 0; m < 4; ++m) {
;                     const unsigned off = E1_OFF(ai, m, bj);
;                     const f32x4 b0 = __builtin_nontemporal_load((const f32x4*)(base + off)), b1 = __builtin_nontemporal_load((const f32x4*)(base + off + 16));
;                     acc[ai][bj][m][0] = b0 + g0 * acc[ai][bj][m][0];
;                     acc[ai][bj][m][1] = b1 + g1 * acc[ai][bj][m][1];
;                     asm volatile("" : "+v"(acc[ai][bj][m][0]), "+v"(acc[ai][bj][m][1]));
;                 }
;             asm volatile("" ::: "memory");
;         }
; #pragma unroll
;         for (int ai = 0; ai < 2; ++ai)
; #pragma unroll
;             for (int m = 0; m < 4; ++m) {
;                 float sq = 0.f;
; #pragma unroll
;                 for (int bj = 0; bj < 2; ++bj)
; #pragma unroll
;                     for (int n = 0; n < 2; ++n) { const f32x4 v = acc[ai][bj][m][n]; sq += (v.x * v.x + v.y * v.y) + (v.z * v.z + v.w * v.w); }
;                 sq += __shfl_xor(sq, 16); sq += __shfl_xor(sq, 32);
;                 if (fq == 0) __hip_atomic_fetch_add(E.rowq + row0 + ai * HALF + m * 16, (1ull << 52) + (unsigned long long)(sq * 65536.0f + 0.5f), __ATOMIC_RELAXED, __HIP_MEMORY_SCOPE_AGENT);
;             }
;         if (!E.fin) {
;             char* outp = (char*)E.out;
; #pragma unroll
;             for (int bj = 0; bj < 2; ++bj)
; #pragma unroll
;                 for (int ai = 0; ai < 2; ++ai)
; #pragma unroll
;                     for (int m = 0; m < 4; ++m) {
;                         const unsigned off = E1_OFF(ai, m, bj);
;                         __builtin_nontemporal_store(acc[ai][bj][m][0], (f32x4*)(outp + off)); __builtin_nontemporal_store(acc[ai][bj][m][1], (f32x4*)(outp + off + 16));
;                     }
;         }
	v_pk_fma_f32 v[2:3], v[2:3], v[178:179], v[220:221]
	v_pk_fma_f32 v[0:1], v[0:1], v[176:177], v[218:219]
	v_add_u32_e32 v173, 0x90000, v144
	global_store_dwordx4 v173, v[24:27], s[86:87] nt
	global_store_dwordx4 v173, v[0:3], s[86:87] offset:16 nt
	v_add_u32_e32 v171, 0x10080, v144
	global_load_dwordx4 v[214:217], v171, s[86:87] nt
	global_load_dwordx4 v[218:221], v171, s[86:87] offset:16 nt
	s_nop 0
	s_waitcnt vmcnt(13)
	v_pk_fma_f32 v[58:59], v[58:59], v[130:131], v[224:225]
	v_pk_fma_f32 v[56:57], v[56:57], v[128:129], v[222:223]
	s_waitcnt vmcnt(12)
	v_pk_fma_f32 v[42:43], v[42:43], v[178:179], v[228:229]
	v_pk_fma_f32 v[40:41], v[40:41], v[176:177], v[226:227]
	v_add_u32_e32 v173, 0xa0000, v144
	global_store_dwordx4 v173, v[56:59], s[86:87] nt
	global_store_dwordx4 v173, v[40:43], s[86:87] offset:16 nt
	v_add_u32_e32 v169, 0x20080, v144
	global_load_dwordx4 v[222:225], v169, s[86:87] nt
	global_load_dwordx4 v[226:229], v169, s[86:87] offset:16 nt
	s_nop 0
	s_waitcnt vmcnt(13)
	v_pk_fma_f32 v[10:11], v[10:11], v[130:131], v[242:243]
	v_pk_fma_f32 v[8:9], v[8:9], v[128:129], v[240:241]
	s_waitcnt vmcnt(12)
	v_pk_fma_f32 v[14:15], v[14:15], v[178:179], v[246:247]
	v_pk_fma_f32 v[12:13], v[12:13], v[176:177], v[244:245]
	v_add_u32_e32 v173, 0xb0000, v144
	global_store_dwordx4 v173, v[8:11], s[86:87] nt
	global_store_dwordx4 v173, v[12:15], s[86:87] offset:16 nt
	v_add_u32_e32 v171, 0x30080, v144
	global_load_dwordx4 v[240:243], v171, s[86:87] nt
	global_load_dwordx4 v[244:247], v171, s[86:87] offset:16 nt
	s_nop 0
	global_load_dwordx4 v[132:135], v[154:155], off offset:128
	global_load_dwordx4 v[128:131], v[154:155], off offset:144
	v_add_u32_e32 v154, 0x10080, v144
	v_xor_b32_e32 v155, 16, v200
	v_cmp_lt_i32_e32 vcc, v155, v157
	s_waitcnt vmcnt(1)
	v_pk_fma_f32 v[34:35], v[34:35], v[134:135], v[188:189]
	v_pk_fma_f32 v[32:33], v[32:33], v[132:133], v[186:187]
	s_waitcnt vmcnt(0)
	v_pk_fma_f32 v[18:19], v[18:19], v[130:131], v[212:213]
	v_pk_fma_f32 v[16:17], v[16:17], v[128:129], v[210:211]
	global_store_dwordx4 v144, v[32:35], s[86:87] offset:128 nt
	global_store_dwordx4 v144, v[16:19], s[86:87] offset:144 nt
	v_add_u32_e32 v169, 0x80080, v144
	global_load_dwordx4 v[186:189], v169, s[86:87] nt
	global_load_dwordx4 v[210:213], v169, s[86:87] offset:16 nt
	v_cndmask_b32_e32 v155, v200, v155, vcc
	v_mul_f32_e32 v161, v33, v33
	v_mul_f32_e32 v163, v35, v35
	v_mul_f32_e32 v165, v17, v17
	v_mul_f32_e32 v167, v19, v19
	v_fmac_f32_e32 v161, v32, v32
	v_fmac_f32_e32 v163, v34, v34
	v_fmac_f32_e32 v165, v16, v16
	v_fmac_f32_e32 v167, v18, v18
	v_add_f32_e32 v161, v161, v163
	v_add_f32_e32 v163, v165, v167
	v_add_f32_e32 v159, v159, v161
	v_lshlrev_b32_e32 v155, 2, v155
	v_add_f32_e32 v159, v163, v159
	ds_bpermute_b32 v161, v155, v159
	v_xor_b32_e32 v163, 32, v200
	v_cmp_lt_i32_e32 vcc, v163, v157
	s_waitcnt lgkmcnt(0)
	v_add_f32_e32 v159, v159, v161
	v_cndmask_b32_e32 v157, v200, v163, vcc
	v_lshlrev_b32_e32 v157, 2, v157
	ds_bpermute_b32 v161, v157, v159
	v_pk_fma_f32 v[66:67], v[66:67], v[134:135], v[216:217]
	v_pk_fma_f32 v[64:65], v[64:65], v[132:133], v[214:215]
	v_pk_fma_f32 v[50:51], v[50:51], v[130:131], v[220:221]
	v_pk_fma_f32 v[48:49], v[48:49], v[128:129], v[218:219]
	v_add_u32_e32 v173, 0x10080, v144
	global_store_dwordx4 v173, v[64:67], s[86:87] nt
	global_store_dwordx4 v173, v[48:51], s[86:87] offset:16 nt
	v_add_u32_e32 v171, 0x90080, v144
	global_load_dwordx4 v[214:217], v171, s[86:87] nt
	global_load_dwordx4 v[218:221], v171, s[86:87] offset:16 nt
	s_nop 0
	v_pk_fma_f32 v[30:31], v[30:31], v[134:135], v[224:225]
	v_pk_fma_f32 v[28:29], v[28:29], v[132:133], v[222:223]
	v_pk_fma_f32 v[6:7], v[6:7], v[130:131], v[228:229]
	v_pk_fma_f32 v[4:5], v[4:5], v[128:129], v[226:227]
	v_add_u32_e32 v173, 0x20080, v144
	global_store_dwordx4 v173, v[28:31], s[86:87] nt
	global_store_dwordx4 v173, v[4:7], s[86:87] offset:16 nt
	v_add_u32_e32 v169, 0xa0080, v144
	global_load_dwordx4 v[222:225], v169, s[86:87] nt
	global_load_dwordx4 v[226:229], v169, s[86:87] offset:16 nt
	s_nop 0
	v_pk_fma_f32 v[70:71], v[70:71], v[134:135], v[242:243]
	v_pk_fma_f32 v[68:69], v[68:69], v[132:133], v[240:241]
	v_pk_fma_f32 v[54:55], v[54:55], v[130:131], v[246:247]
	v_pk_fma_f32 v[52:53], v[52:53], v[128:129], v[244:245]
	v_add_u32_e32 v173, 0x30080, v144
	global_store_dwordx4 v173, v[68:71], s[86:87] nt
	global_store_dwordx4 v173, v[52:55], s[86:87] offset:16 nt
	v_add_u32_e32 v171, 0xb0080, v144
	global_load_dwordx4 v[240:243], v171, s[86:87] nt
	global_load_dwordx4 v[244:247], v171, s[86:87] offset:16 nt
	v_add_u32_e32 v176, 0x90080, v144
	v_add_u32_e32 v178, 0xa0080, v144
	s_waitcnt vmcnt(13)
	v_pk_fma_f32 v[86:87], v[86:87], v[134:135], v[188:189]
	v_pk_fma_f32 v[84:85], v[84:85], v[132:133], v[186:187]
	s_waitcnt vmcnt(12)
	v_pk_fma_f32 v[78:79], v[78:79], v[130:131], v[212:213]
	v_pk_fma_f32 v[76:77], v[76:77], v[128:129], v[210:211]
	v_add_u32_e32 v173, 0x80080, v144
	global_store_dwordx4 v173, v[84:87], s[86:87] nt
	global_store_dwordx4 v173, v[76:79], s[86:87] offset:16 nt
	s_nop 0
	s_waitcnt vmcnt(11)
	v_pk_fma_f32 v[102:103], v[102:103], v[134:135], v[216:217]
	v_pk_fma_f32 v[100:101], v[100:101], v[132:133], v[214:215]
	s_waitcnt vmcnt(10)
	v_pk_fma_f32 v[94:95], v[94:95], v[130:131], v[220:221]
	v_pk_fma_f32 v[92:93], v[92:93], v[128:129], v[218:219]
	v_add_u32_e32 v173, 0x90080, v144
	global_store_dwordx4 v173, v[100:103], s[86:87] nt
	global_store_dwordx4 v173, v[92:95], s[86:87] offset:16 nt
	s_nop 0
	s_waitcnt vmcnt(9)
	v_pk_fma_f32 v[118:119], v[118:119], v[134:135], v[224:225]
	v_pk_fma_f32 v[116:117], v[116:117], v[132:133], v[222:223]
	s_waitcnt vmcnt(8)
	v_pk_fma_f32 v[110:111], v[110:111], v[130:131], v[228:229]
	v_pk_fma_f32 v[108:109], v[108:109], v[128:129], v[226:227]
	v_add_u32_e32 v173, 0xa0080, v144
	global_store_dwordx4 v173, v[116:119], s[86:87] nt
	global_store_dwordx4 v173, v[108:111], s[86:87] offset:16 nt
	s_nop 0
	s_waitcnt vmcnt(7)
	v_pk_fma_f32 v[126:127], v[126:127], v[134:135], v[242:243]
	v_pk_fma_f32 v[124:125], v[124:125], v[132:133], v[240:241]
	s_waitcnt vmcnt(6)
	v_pk_fma_f32 v[122:123], v[122:123], v[130:131], v[246:247]
	v_pk_fma_f32 v[120:121], v[120:121], v[128:129], v[244:245]
	v_add_u32_e32 v173, 0xb0080, v144
	global_store_dwordx4 v173, v[124:127], s[86:87] nt
	global_store_dwordx4 v173, v[120:123], s[86:87] offset:16 nt
	s_waitcnt vmcnt(0)
	v_lshl_add_u64 v[128:129], v[184:185], 3, s[2:3]
	s_and_saveexec_b64 s[8:9], s[4:5]
	s_cbranch_execz .LBB0_1001
	s_waitcnt lgkmcnt(0)
	v_add_f32_e32 v130, v159, v161
	v_fma_f32 v130, v130, s58, 0.5
	v_trunc_f32_e32 v130, v130
	v_mul_f32_e32 v131, 0x2f800000, v130
	v_floor_f32_e32 v131, v131
	v_fmac_f32_e32 v130, 0xcf800000, v131
	v_cvt_u32_f32_e32 v131, v131
	v_cvt_u32_f32_e32 v130, v130
	v_add_u32_e32 v131, 0x100000, v131
	global_atomic_add_x2 v[128:129], v[130:131], off

; template <int MODE> DI void epilogue(const Epi& E, f32x4 (&acc)[2][2][4][2], const Unit& u, int wr, int wc, int fr, int fq) {
;     ...
;         if (!E.fin) {
;             char* outp = (char*)E.out;
; #pragma unroll
;             for (int bj = 0; bj < 2; ++bj)
; #pragma unroll
;                 for (int ai = 0; ai < 2; ++ai)
; #pragma unroll
;                     for (int m = 0; m < 4; ++m) {
;                         const unsigned off = E1_OFF(ai, m, bj);
;                         __builtin_nontemporal_store(acc[ai][bj][m][0], (f32x4*)(outp + off)); __builtin_nontemporal_store(acc[ai][bj][m][1], (f32x4*)(outp + off + 16));
;                     }
;         }
.LBB0_1015:
	s_or_b64 exec, exec, s[8:9]
	v_readlane_b32 s72, v254, 38
	v_readlane_b32 s86, v254, 52
	v_readlane_b32 s87, v254, 53
	v_mov_b32_e32 v167, v145
	v_mov_b32_e32 v171, v145
	v_mov_b32_e32 v175, v145
	v_mov_b32_e32 v157, v145
	v_mov_b32_e32 v161, v145
	s_waitcnt lgkmcnt(0)
	v_lshl_add_u64 v[130:131], s[86:87], 0, v[144:145]
	v_lshl_add_u64 v[132:133], s[86:87], 0, v[166:167]
	v_lshl_add_u64 v[134:135], s[86:87], 0, v[170:171]
	v_lshl_add_u64 v[184:185], s[86:87], 0, v[174:175]
	v_lshl_add_u64 v[186:187], s[86:87], 0, v[156:157]
	v_lshl_add_u64 v[188:189], s[86:87], 0, v[160:161]
	v_mov_b32_e32 v163, v145
	v_mov_b32_e32 v169, v145
	v_mov_b32_e32 v155, v145
	v_mov_b32_e32 v159, v145
	v_mov_b32_e32 v165, v145
	v_mov_b32_e32 v173, v145
	v_mov_b32_e32 v177, v145
	v_mov_b32_e32 v179, v145
	v_mov_b32_e32 v183, v145
	s_mov_b32 s35, 0
	v_readlane_b32 s73, v254, 39
	v_readlane_b32 s74, v254, 40
	v_readlane_b32 s75, v254, 41
	v_readlane_b32 s76, v254, 42
	v_readlane_b32 s77, v254, 43
	v_readlane_b32 s78, v254, 44
	v_readlane_b32 s79, v254, 45
	v_readlane_b32 s80, v254, 46
	v_readlane_b32 s81, v254, 47
	v_readlane_b32 s82, v254, 48
	v_readlane_b32 s83, v254, 49
	v_readlane_b32 s84, v254, 50
	v_readlane_b32 s85, v254, 51
	v_lshl_add_u64 v[194:195], s[86:87], 0, v[162:163]
	v_lshl_add_u64 v[202:203], s[86:87], 0, v[168:169]
	v_lshl_add_u64 v[204:205], s[86:87], 0, v[154:155]
	v_lshl_add_u64 v[206:207], s[86:87], 0, v[158:159]
	v_lshl_add_u64 v[208:209], s[86:87], 0, v[164:165]
	v_lshl_add_u64 v[210:211], s[86:87], 0, v[172:173]
	v_lshl_add_u64 v[212:213], s[86:87], 0, v[176:177]
	v_lshl_add_u64 v[214:215], s[86:87], 0, v[178:179]
	v_lshl_add_u64 v[216:217], s[86:87], 0, v[182:183]
	s_branch .LBB0_1017

; #define LAS __attribute__((address_space(3)))
; __global__ void __launch_bounds__(512, 2) fwd_megakernel(Args args) {
;     extern __shared__ __attribute__((aligned(16))) unsigned char lds_raw[];
;     LAS unsigned char* lds = (LAS unsigned char*)lds_raw;
	.amdhsa_kernel _Z14fwd_megakernel4Args
		.amdhsa_group_segment_fixed_size 0
		.amdhsa_private_segment_fixed_size 0
		.amdhsa_kernarg_size 456
		.amdhsa_user_sgpr_count 2
		.amdhsa_user_sgpr_dispatch_ptr 0
		.amdhsa_user_sgpr_queue_ptr 0
		.amdhsa_user_sgpr_kernarg_segment_ptr 1
		.amdhsa_user_sgpr_dispatch_id 0
		.amdhsa_user_sgpr_kernarg_preload_length 0
		.amdhsa_user_sgpr_kernarg_preload_offset 0
		.amdhsa_user_sgpr_private_segment_size 0
		.amdhsa_uses_dynamic_stack 0
		.amdhsa_enable_private_segment 0
		.amdhsa_system_sgpr_workgroup_id_x 1
		.amdhsa_system_sgpr_workgroup_id_y 0
		.amdhsa_system_sgpr_workgroup_id_z 0
		.amdhsa_system_sgpr_workgroup_info 0
		.amdhsa_system_vgpr_workitem_id 2
		.amdhsa_next_free_vgpr 256
		.amdhsa_next_free_sgpr 100
		.amdhsa_accum_offset 256
		.amdhsa_reserve_vcc 1
		.amdhsa_float_round_mode_32 0
		.amdhsa_float_round_mode_16_64 0
		.amdhsa_float_denorm_mode_32 3
		.amdhsa_float_denorm_mode_16_64 3
		.amdhsa_dx10_clamp 1
		.amdhsa_ieee_mode 1
		.amdhsa_fp16_overflow 0
		.amdhsa_tg_split 0
		.amdhsa_exception_fp_ieee_invalid_op 0
		.amdhsa_exception_fp_denorm_src 0
		.amdhsa_exception_fp_ieee_div_zero 0
		.amdhsa_exception_fp_ieee_overflow 0
		.amdhsa_exception_fp_ieee_underflow 0
		.amdhsa_exception_fp_ieee_inexact 0
		.amdhsa_exception_int_div_zero 0
	.end_amdhsa_kernel

; #define LAS __attribute__((address_space(3)))
; __global__ void __launch_bounds__(512, 2) fwd_megakernel(Args args) {
;     extern __shared__ __attribute__((aligned(16))) unsigned char lds_raw[];
;     LAS unsigned char* lds = (LAS unsigned char*)lds_raw;
amdhsa.kernels:
  - .agpr_count:     0
    .args:
      - .offset:         0
        .size:           200
        .value_kind:     by_value
      - .offset:         200
        .size:           4
        .value_kind:     hidden_block_count_x
      - .offset:         204
        .size:           4
        .value_kind:     hidden_block_count_y
      - .offset:         208
        .size:           4
        .value_kind:     hidden_block_count_z
      - .offset:         212
        .size:           2
        .value_kind:     hidden_group_size_x
      - .offset:         214
        .size:           2
        .value_kind:     hidden_group_size_y
      - .offset:         216
        .size:           2
        .value_kind:     hidden_group_size_z
      - .offset:         218
        .size:           2
        .value_kind:     hidden_remainder_x
      - .offset:         220
        .size:           2
        .value_kind:     hidden_remainder_y
      - .offset:         222
        .size:           2
        .value_kind:     hidden_remainder_z
      - .offset:         240
        .size:           8
        .value_kind:     hidden_global_offset_x
      - .offset:         248
        .size:           8
        .value_kind:     hidden_global_offset_y
      - .offset:         256
        .size:           8
        .value_kind:     hidden_global_offset_z
      - .offset:         264
        .size:           2
        .value_kind:     hidden_grid_dims
      - .offset:         288
        .size:           8
        .value_kind:     hidden_multigrid_sync_arg
      - .offset:         320
        .size:           4
        .value_kind:     hidden_dynamic_lds_size
    .group_segment_fixed_size: 0
    .kernarg_segment_align: 8
    .kernarg_segment_size: 456
    .language:       OpenCL C
    .language_version:
      - 2
      - 0
    .max_flat_workgroup_size: 512
    .name:           _Z14fwd_megakernel4Args
    .private_segment_fixed_size: 0
    .sgpr_count:     106
    .sgpr_spill_count: 131
    .symbol:         _Z14fwd_megakernel4Args.kd
    .uniform_work_group_size: 1
    .uses_dynamic_stack: false
    .vgpr_count:     256
    .vgpr_spill_count: 0
    .wavefront_size: 64
